# both fused out-proj epilogues: residual-stream loads of each row group issued together with counted waits
# speedup vs baseline: 1.0122x; 1.0065x over previous
; #define PG8_LAS __attribute__((address_space(3)))
;     __device__ __forceinline__ void fused(f32x4 (&acc)[2][2][4][2], const Unit& u, int wr, int wc, int fr, int fq, PG8_LAS unsigned char* lds, int wid, int lane) const {
;         const int row0 = u.pm * BM + wr * 64 + fr; const int col0 = u.pn * BM + wc * 32 + 4 * fq;
;         const int b = (u.pm * BM) >> 11;
;         PG8_LAS float* P = (PG8_LAS float*)lds; PG8_LAS float* S = P + 1024;
;         f32x4 gt[2][2];
; #pragma unroll
;         for (int bj = 0; bj < 2; ++bj)
; #pragma unroll
;             for (int n = 0; n < 2; ++n) gt[bj][n] = *(const f32x4*)(modf + (size_t)b * 3072 + 2048 + col0 + bj * HALF + 16 * n);
; #pragma unroll
;         for (int ai = 0; ai < 2; ++ai)
; #pragma unroll
;             for (int m = 0; m < 4; ++m) { const size_t ro = (size_t)(row0 + ai * HALF + m * 16) * 1024 + col0; float s = 0.f;
; #pragma unroll
;                 for (int bj = 0; bj < 2; ++bj)
; #pragma unroll
;                     for (int n = 0; n < 2; ++n) { const f32x4 xi = __builtin_nontemporal_load((const f32x4*)(xin + ro + bj * HALF + 16 * n));
;                         const f32x4 v = xi + gt[bj][n] * acc[ai][bj][m][n]; acc[ai][bj][m][n] = v;
;                         s += (v[0] * v[0] + v[1] * v[1]) + (v[2] * v[2] + v[3] * v[3]); }
;                 s += __shfl_xor(s, 16); s += __shfl_xor(s, 32);
;                 if (fq == 0) P[(ai * HALF + wr * 64 + m * 16 + fr) * 4 + wc] = s; }
.LBB0_669:
	v_readlane_b32 s30, v255, 27
	v_readlane_b32 s31, v255, 28
	s_mul_i32 s2, s30, 0x18000
	v_readlane_b32 s30, v253, 48
	v_readlane_b32 s31, v253, 49
	s_add_u32 s2, s30, s2
	s_addc_u32 s4, s31, 0
	s_lshl_b32 s30, s20, 8
	s_lshl_b32 s21, s27, 5
	s_add_i32 s33, s30, s5
	s_lshl_b32 s30, s26, 8
	s_or_b32 s21, s30, s21
	v_lshrrev_b32_e32 v76, 2, v191
	v_and_or_b32 v160, v76, 12, s21
	s_ashr_i32 s21, s20, 3
	s_mul_hi_i32 s31, s21, 0x3000
	s_mulk_i32 s21, 0x3000
	s_add_u32 s30, s2, s21
	v_ashrrev_i32_e32 v161, 31, v160
	s_addc_u32 s31, s4, s31
	v_lshlrev_b64 v[148:149], 2, v[160:161]
	v_lshl_add_u64 v[76:77], s[30:31], 0, v[148:149]
	s_mov_b64 s[30:31], 0x2000
	s_movk_i32 s2, 0x2000
	v_lshl_add_u64 v[78:79], v[76:77], 0, s[30:31]
	v_add_co_u32_e32 v76, vcc, s2, v76
	v_and_b32_e32 v151, 64, v224
	s_nop 0
	v_addc_co_u32_e32 v77, vcc, 0, v77, vcc
	v_xor_b32_e32 v150, 16, v224
	v_add_u32_e32 v151, 64, v151
	v_cmp_lt_i32_e32 vcc, v150, v151
	v_or_b32_e32 v164, s33, v168
	v_ashrrev_i32_e32 v165, 31, v164
	v_cndmask_b32_e32 v150, v224, v150, vcc
	v_lshlrev_b32_e32 v170, 2, v150
	v_xor_b32_e32 v150, 32, v224
	v_cmp_lt_i32_e32 vcc, v150, v151
	s_waitcnt vmcnt(0)
	s_barrier
	global_load_dwordx4 v[100:103], v[76:77], off
	global_load_dwordx4 v[92:95], v[78:79], off offset:64
	global_load_dwordx4 v[84:87], v[78:79], off offset:512
	s_nop 0
	global_load_dwordx4 v[76:79], v[78:79], off offset:576
	v_cndmask_b32_e32 v150, v224, v150, vcc
	v_lshlrev_b32_e32 v171, 2, v150
	v_lshlrev_b64 v[150:151], 12, v[164:165]
	v_lshl_add_u64 v[154:155], s[18:19], 0, v[150:151]
	v_lshl_add_u64 v[158:159], v[154:155], 0, v[148:149]
	global_load_dwordx4 v[212:215], v[158:159], off nt
	global_load_dwordx4 v[216:219], v[158:159], off offset:64 nt
	global_load_dwordx4 v[220:223], v[158:159], off offset:512 nt
	global_load_dwordx4 v[242:245], v[158:159], off offset:576 nt
	s_lshl_b32 s2, s27, 2
	v_and_b32_e32 v169, 63, v191
	s_add_i32 s2, s2, 0
	v_cmp_gt_u32_e32 vcc, 16, v169
	v_lshl_add_u32 v172, v152, 4, s2
	s_waitcnt vmcnt(3)
	v_pk_fma_f32 v[146:147], v[146:147], v[102:103], v[214:215]
	v_pk_fma_f32 v[144:145], v[144:145], v[100:101], v[212:213]
	v_mul_f32_e32 v154, v147, v147
	v_mul_f32_e32 v153, v145, v145
	v_fmac_f32_e32 v153, v144, v144
	v_fmac_f32_e32 v154, v146, v146
	v_add_f32_e32 v153, v153, v154
	s_waitcnt vmcnt(2)
	v_pk_fma_f32 v[142:143], v[142:143], v[94:95], v[218:219]
	v_pk_fma_f32 v[140:141], v[140:141], v[92:93], v[216:217]
	v_mul_f32_e32 v155, v143, v143
	v_mul_f32_e32 v154, v141, v141
	v_fmac_f32_e32 v154, v140, v140
	v_fmac_f32_e32 v155, v142, v142
	v_add_f32_e32 v154, v154, v155
	v_add_f32_e32 v153, v153, v154
	s_waitcnt vmcnt(1)
	v_pk_fma_f32 v[138:139], v[138:139], v[86:87], v[222:223]
	v_pk_fma_f32 v[136:137], v[136:137], v[84:85], v[220:221]
	v_mul_f32_e32 v155, v139, v139
	v_mul_f32_e32 v154, v137, v137
	v_fmac_f32_e32 v154, v136, v136
	v_fmac_f32_e32 v155, v138, v138
	v_add_f32_e32 v154, v154, v155
	v_add_f32_e32 v153, v153, v154
	s_waitcnt vmcnt(0)
	v_pk_fma_f32 v[134:135], v[134:135], v[78:79], v[244:245]
	v_pk_fma_f32 v[132:133], v[132:133], v[76:77], v[242:243]
	v_mul_f32_e32 v155, v135, v135
	v_mul_f32_e32 v154, v133, v133
	v_fmac_f32_e32 v154, v132, v132
	v_fmac_f32_e32 v155, v134, v134
	v_add_f32_e32 v154, v154, v155
	v_add_f32_e32 v153, v153, v154
	ds_bpermute_b32 v154, v170, v153
	s_waitcnt lgkmcnt(0)
	v_add_f32_e32 v153, v153, v154
	ds_bpermute_b32 v154, v171, v153
	s_and_saveexec_b64 s[30:31], vcc
	s_cbranch_execz .LBB0_671
	s_waitcnt lgkmcnt(0)
	v_add_f32_e32 v152, v153, v154
	ds_write_b32 v172, v152
.LBB0_671:
	s_or_b64 exec, exec, s[30:31]
	v_or_b32_e32 v152, 16, v164
	v_ashrrev_i32_e32 v153, 31, v152
	v_lshlrev_b64 v[152:153], 12, v[152:153]
	s_waitcnt lgkmcnt(0)
	v_lshl_add_u64 v[154:155], s[18:19], 0, v[152:153]
	v_lshl_add_u64 v[158:159], v[160:161], 2, v[154:155]
	global_load_dwordx4 v[212:215], v[158:159], off nt
	global_load_dwordx4 v[216:219], v[158:159], off offset:64 nt
	global_load_dwordx4 v[220:223], v[158:159], off offset:512 nt
	global_load_dwordx4 v[242:245], v[158:159], off offset:576 nt
	s_waitcnt vmcnt(3)
	v_pk_fma_f32 v[130:131], v[130:131], v[102:103], v[214:215]
	v_pk_fma_f32 v[128:129], v[128:129], v[100:101], v[212:213]
	v_mul_f32_e32 v155, v131, v131
	v_mul_f32_e32 v154, v129, v129
	v_fmac_f32_e32 v154, v128, v128
	v_fmac_f32_e32 v155, v130, v130
	v_add_f32_e32 v162, v154, v155
	s_waitcnt vmcnt(2)
	v_pk_fma_f32 v[126:127], v[126:127], v[94:95], v[218:219]
	v_pk_fma_f32 v[124:125], v[124:125], v[92:93], v[216:217]
	v_mul_f32_e32 v155, v127, v127
	v_mul_f32_e32 v154, v125, v125
	v_fmac_f32_e32 v154, v124, v124
	v_fmac_f32_e32 v155, v126, v126
	v_add_f32_e32 v154, v154, v155
	v_add_f32_e32 v162, v162, v154
	s_waitcnt vmcnt(1)
	v_pk_fma_f32 v[122:123], v[122:123], v[86:87], v[222:223]
	v_pk_fma_f32 v[120:121], v[120:121], v[84:85], v[220:221]
	v_mul_f32_e32 v155, v123, v123
	v_mul_f32_e32 v154, v121, v121
	v_fmac_f32_e32 v154, v120, v120
	v_fmac_f32_e32 v155, v122, v122
	v_add_f32_e32 v154, v154, v155
	v_add_f32_e32 v162, v162, v154
	s_waitcnt vmcnt(0)
	v_pk_fma_f32 v[118:119], v[118:119], v[78:79], v[244:245]
	v_pk_fma_f32 v[154:155], v[116:117], v[76:77], v[242:243]
	v_mul_f32_e32 v117, v119, v119
	v_mul_f32_e32 v116, v155, v155
	v_fmac_f32_e32 v116, v154, v154
	v_fmac_f32_e32 v117, v118, v118
	v_add_f32_e32 v116, v116, v117
	v_add_f32_e32 v116, v162, v116
	ds_bpermute_b32 v117, v170, v116
	s_waitcnt lgkmcnt(0)
	v_add_f32_e32 v116, v116, v117
	ds_bpermute_b32 v117, v171, v116
	s_and_saveexec_b64 s[30:31], vcc
	s_cbranch_execz .LBB0_673
	s_waitcnt lgkmcnt(0)
	v_add_f32_e32 v116, v116, v117
	ds_write_b32 v172, v116 offset:256

;     __device__ __forceinline__ void fused(f32x4 (&acc)[2][2][4][2], const Unit& u, int wr, int wc, int fr, int fq, PG8_LAS unsigned char* lds, int wid, int lane) const {
;     ...
;         for (int ai = 0; ai < 2; ++ai)
; #pragma unroll
;             for (int m = 0; m < 4; ++m) { const size_t ro = (size_t)(row0 + ai * HALF + m * 16) * 1024 + col0; float s = 0.f;
; #pragma unroll
;                 for (int bj = 0; bj < 2; ++bj)
; #pragma unroll
;                     for (int n = 0; n < 2; ++n) { const f32x4 xi = __builtin_nontemporal_load((const f32x4*)(xin + ro + bj * HALF + 16 * n));
;                         const f32x4 v = xi + gt[bj][n] * acc[ai][bj][m][n]; acc[ai][bj][m][n] = v;
;                         s += (v[0] * v[0] + v[1] * v[1]) + (v[2] * v[2] + v[3] * v[3]); }
;                 s += __shfl_xor(s, 16); s += __shfl_xor(s, 32);
;                 if (fq == 0) P[(ai * HALF + wr * 64 + m * 16 + fr) * 4 + wc] = s; }
.LBB0_675:
	s_or_b64 exec, exec, s[30:31]
	v_or_b32_e32 v96, 48, v164
	s_waitcnt lgkmcnt(0)
	v_ashrrev_i32_e32 v97, 31, v96
	v_lshlrev_b64 v[96:97], 12, v[96:97]
	v_lshl_add_u64 v[158:159], s[18:19], 0, v[96:97]
	v_lshl_add_u64 v[158:159], v[160:161], 2, v[158:159]
	global_load_dwordx4 v[212:215], v[158:159], off nt
	global_load_dwordx4 v[216:219], v[158:159], off offset:64 nt
	global_load_dwordx4 v[220:223], v[158:159], off offset:512 nt
	global_load_dwordx4 v[242:245], v[158:159], off offset:576 nt
	s_waitcnt vmcnt(3)
	v_pk_fma_f32 v[90:91], v[90:91], v[102:103], v[214:215]
	v_pk_fma_f32 v[88:89], v[88:89], v[100:101], v[212:213]
	v_mul_f32_e32 v162, v89, v89
	v_mul_f32_e32 v163, v91, v91
	v_fmac_f32_e32 v162, v88, v88
	v_fmac_f32_e32 v163, v90, v90
	v_add_f32_e32 v162, v162, v163
	s_waitcnt vmcnt(2)
	v_pk_fma_f32 v[82:83], v[82:83], v[94:95], v[218:219]
	v_pk_fma_f32 v[80:81], v[80:81], v[92:93], v[216:217]
	v_mul_f32_e32 v163, v81, v81
	v_mul_f32_e32 v166, v83, v83
	v_fmac_f32_e32 v163, v80, v80
	v_fmac_f32_e32 v166, v82, v82
	v_add_f32_e32 v163, v163, v166
	v_add_f32_e32 v162, v162, v163
	s_waitcnt vmcnt(1)
	v_pk_fma_f32 v[74:75], v[74:75], v[86:87], v[222:223]
	v_pk_fma_f32 v[72:73], v[72:73], v[84:85], v[220:221]
	v_mul_f32_e32 v163, v73, v73
	v_mul_f32_e32 v166, v75, v75
	v_fmac_f32_e32 v163, v72, v72
	v_fmac_f32_e32 v166, v74, v74
	v_add_f32_e32 v163, v163, v166
	v_add_f32_e32 v162, v162, v163
	s_waitcnt vmcnt(0)
	v_pk_fma_f32 v[70:71], v[70:71], v[78:79], v[244:245]
	v_pk_fma_f32 v[68:69], v[68:69], v[76:77], v[242:243]
	v_mul_f32_e32 v159, v71, v71
	v_mul_f32_e32 v158, v69, v69
	v_fmac_f32_e32 v158, v68, v68
	v_fmac_f32_e32 v159, v70, v70
	v_add_f32_e32 v158, v158, v159
	v_add_f32_e32 v158, v162, v158
	ds_bpermute_b32 v159, v170, v158
	s_waitcnt lgkmcnt(0)
	v_add_f32_e32 v158, v158, v159
	ds_bpermute_b32 v159, v171, v158
	s_and_saveexec_b64 s[30:31], vcc
	s_cbranch_execz .LBB0_677
	s_waitcnt lgkmcnt(0)
	v_add_f32_e32 v158, v158, v159
	ds_write_b32 v172, v158 offset:768
.LBB0_677:
	s_or_b64 exec, exec, s[30:31]
	v_lshlrev_b64 v[162:163], 12, v[164:165]
	s_mov_b64 s[30:31], 0x80000
	s_waitcnt lgkmcnt(0)
	v_lshl_add_u64 v[158:159], v[162:163], 0, s[30:31]
	v_lshl_add_u64 v[166:167], s[18:19], 0, v[158:159]
	v_lshl_add_u64 v[166:167], v[160:161], 2, v[166:167]
	global_load_dwordx4 v[212:215], v[166:167], off nt
	global_load_dwordx4 v[216:219], v[166:167], off offset:64 nt
	global_load_dwordx4 v[220:223], v[166:167], off offset:512 nt
	global_load_dwordx4 v[242:245], v[166:167], off offset:576 nt
	s_waitcnt vmcnt(3)
	v_pk_fma_f32 v[66:67], v[66:67], v[102:103], v[214:215]
	v_pk_fma_f32 v[64:65], v[64:65], v[100:101], v[212:213]
	v_mul_f32_e32 v174, v67, v67
	v_mul_f32_e32 v173, v65, v65
	v_fmac_f32_e32 v173, v64, v64
	v_fmac_f32_e32 v174, v66, v66
	v_add_f32_e32 v173, v173, v174
	s_waitcnt vmcnt(2)
	v_pk_fma_f32 v[62:63], v[62:63], v[94:95], v[218:219]
	v_pk_fma_f32 v[60:61], v[60:61], v[92:93], v[216:217]
	v_mul_f32_e32 v175, v63, v63
	v_mul_f32_e32 v174, v61, v61
	v_fmac_f32_e32 v174, v60, v60
	v_fmac_f32_e32 v175, v62, v62
	v_add_f32_e32 v174, v174, v175
	v_add_f32_e32 v173, v173, v174
	s_waitcnt vmcnt(1)
	v_pk_fma_f32 v[58:59], v[58:59], v[86:87], v[222:223]
	v_pk_fma_f32 v[56:57], v[56:57], v[84:85], v[220:221]
	v_mul_f32_e32 v175, v59, v59
	v_mul_f32_e32 v174, v57, v57
	v_fmac_f32_e32 v174, v56, v56
	v_fmac_f32_e32 v175, v58, v58
	v_add_f32_e32 v174, v174, v175
	v_add_f32_e32 v173, v173, v174
	s_waitcnt vmcnt(0)
	v_pk_fma_f32 v[54:55], v[54:55], v[78:79], v[244:245]
	v_pk_fma_f32 v[52:53], v[52:53], v[76:77], v[242:243]
	v_mul_f32_e32 v167, v55, v55
	v_mul_f32_e32 v166, v53, v53
	v_fmac_f32_e32 v166, v52, v52
	v_fmac_f32_e32 v167, v54, v54
	v_add_f32_e32 v166, v166, v167
	v_add_f32_e32 v166, v173, v166
	ds_bpermute_b32 v167, v170, v166
	s_waitcnt lgkmcnt(0)
	v_add_f32_e32 v166, v166, v167
	ds_bpermute_b32 v167, v171, v166
	s_and_saveexec_b64 s[30:31], vcc
	s_cbranch_execz .LBB0_679
	s_waitcnt lgkmcnt(0)
	v_add_f32_e32 v166, v166, v167
	ds_write_b32 v172, v166 offset:2048
;     __device__ __forceinline__ void fused(f32x4 (&acc)[2][2][4][2], const Unit& u, int wr, int wc, int fr, int fq, PG8_LAS unsigned char* lds, int wid, int lane) const {
;     ...
;         for (int ai = 0; ai < 2; ++ai)
; #pragma unroll
;             for (int m = 0; m < 4; ++m) { const size_t ro = (size_t)(row0 + ai * HALF + m * 16) * 1024 + col0; float s = 0.f;
; #pragma unroll
;                 for (int bj = 0; bj < 2; ++bj)
; #pragma unroll
;                     for (int n = 0; n < 2; ++n) { const f32x4 xi = __builtin_nontemporal_load((const f32x4*)(xin + ro + bj * HALF + 16 * n));
;                         const f32x4 v = xi + gt[bj][n] * acc[ai][bj][m][n]; acc[ai][bj][m][n] = v;
;                         s += (v[0] * v[0] + v[1] * v[1]) + (v[2] * v[2] + v[3] * v[3]); }
;                 s += __shfl_xor(s, 16); s += __shfl_xor(s, 32);
;                 if (fq == 0) P[(ai * HALF + wr * 64 + m * 16 + fr) * 4 + wc] = s; }
.LBB0_679:
	s_or_b64 exec, exec, s[30:31]
	s_mov_b64 s[30:31], 0x90000
	v_lshl_add_u64 v[162:163], v[162:163], 0, s[30:31]
	s_waitcnt lgkmcnt(0)
	v_lshl_add_u64 v[166:167], s[18:19], 0, v[162:163]
	v_lshl_add_u64 v[166:167], v[160:161], 2, v[166:167]
	global_load_dwordx4 v[212:215], v[166:167], off nt
	global_load_dwordx4 v[216:219], v[166:167], off offset:64 nt
	global_load_dwordx4 v[220:223], v[166:167], off offset:512 nt
	global_load_dwordx4 v[242:245], v[166:167], off offset:576 nt
	s_waitcnt vmcnt(3)
	v_pk_fma_f32 v[50:51], v[50:51], v[102:103], v[214:215]
	v_pk_fma_f32 v[48:49], v[48:49], v[100:101], v[212:213]
	v_mul_f32_e32 v174, v51, v51
	v_mul_f32_e32 v173, v49, v49
	v_fmac_f32_e32 v173, v48, v48
	v_fmac_f32_e32 v174, v50, v50
	v_add_f32_e32 v173, v173, v174
	s_waitcnt vmcnt(2)
	v_pk_fma_f32 v[46:47], v[46:47], v[94:95], v[218:219]
	v_pk_fma_f32 v[44:45], v[44:45], v[92:93], v[216:217]
	v_mul_f32_e32 v175, v47, v47
	v_mul_f32_e32 v174, v45, v45
	v_fmac_f32_e32 v174, v44, v44
	v_fmac_f32_e32 v175, v46, v46
	v_add_f32_e32 v174, v174, v175
	v_add_f32_e32 v173, v173, v174
	s_waitcnt vmcnt(1)
	v_pk_fma_f32 v[42:43], v[42:43], v[86:87], v[222:223]
	v_pk_fma_f32 v[40:41], v[40:41], v[84:85], v[220:221]
	v_mul_f32_e32 v175, v43, v43
	v_mul_f32_e32 v174, v41, v41
	v_fmac_f32_e32 v174, v40, v40
	v_fmac_f32_e32 v175, v42, v42
	v_add_f32_e32 v174, v174, v175
	v_add_f32_e32 v173, v173, v174
	s_waitcnt vmcnt(0)
	v_pk_fma_f32 v[38:39], v[38:39], v[78:79], v[244:245]
	v_pk_fma_f32 v[36:37], v[36:37], v[76:77], v[242:243]
	v_mul_f32_e32 v167, v39, v39
	v_mul_f32_e32 v166, v37, v37
	v_fmac_f32_e32 v166, v36, v36
	v_fmac_f32_e32 v167, v38, v38
	v_add_f32_e32 v166, v166, v167
	v_add_f32_e32 v166, v173, v166
	ds_bpermute_b32 v167, v170, v166
	s_waitcnt lgkmcnt(0)
	v_add_f32_e32 v166, v166, v167
	ds_bpermute_b32 v167, v171, v166
	s_and_saveexec_b64 s[30:31], vcc
	s_cbranch_execz .LBB0_681
	s_waitcnt lgkmcnt(0)
	v_add_f32_e32 v166, v166, v167
	ds_write_b32 v172, v166 offset:2304
.LBB0_681:
	s_or_b64 exec, exec, s[30:31]
	s_waitcnt lgkmcnt(0)
	v_lshlrev_b64 v[166:167], 12, v[164:165]
	s_mov_b64 s[30:31], 0xa0000
	v_lshl_add_u64 v[164:165], v[166:167], 0, s[30:31]
	v_lshl_add_u64 v[174:175], s[18:19], 0, v[164:165]
	v_lshl_add_u64 v[178:179], v[160:161], 2, v[174:175]
	global_load_dwordx4 v[212:215], v[178:179], off nt
	global_load_dwordx4 v[216:219], v[178:179], off offset:64 nt
	global_load_dwordx4 v[220:223], v[178:179], off offset:512 nt
	global_load_dwordx4 v[242:245], v[178:179], off offset:576 nt
	s_waitcnt vmcnt(3)
	v_pk_fma_f32 v[34:35], v[34:35], v[102:103], v[214:215]
	v_pk_fma_f32 v[32:33], v[32:33], v[100:101], v[212:213]
	v_mul_f32_e32 v174, v35, v35
	v_mul_f32_e32 v173, v33, v33
	v_fmac_f32_e32 v173, v32, v32
	v_fmac_f32_e32 v174, v34, v34
	v_add_f32_e32 v173, v173, v174
	s_waitcnt vmcnt(2)
	v_pk_fma_f32 v[30:31], v[30:31], v[94:95], v[218:219]
	v_pk_fma_f32 v[28:29], v[28:29], v[92:93], v[216:217]
	v_mul_f32_e32 v175, v31, v31
	v_mul_f32_e32 v174, v29, v29
	v_fmac_f32_e32 v174, v28, v28
	v_fmac_f32_e32 v175, v30, v30
	v_add_f32_e32 v174, v174, v175
	v_add_f32_e32 v173, v173, v174
	s_waitcnt vmcnt(1)
	v_pk_fma_f32 v[26:27], v[26:27], v[86:87], v[222:223]
	v_pk_fma_f32 v[24:25], v[24:25], v[84:85], v[220:221]
	v_mul_f32_e32 v175, v27, v27
	v_mul_f32_e32 v174, v25, v25
	v_fmac_f32_e32 v174, v24, v24
	v_fmac_f32_e32 v175, v26, v26
	v_add_f32_e32 v174, v174, v175
	v_add_f32_e32 v173, v173, v174
	s_waitcnt vmcnt(0)
	v_pk_fma_f32 v[22:23], v[22:23], v[78:79], v[244:245]
	v_pk_fma_f32 v[20:21], v[20:21], v[76:77], v[242:243]
	v_mul_f32_e32 v175, v23, v23
	v_mul_f32_e32 v174, v21, v21
	v_fmac_f32_e32 v174, v20, v20
	v_fmac_f32_e32 v175, v22, v22
	v_add_f32_e32 v174, v174, v175
	v_add_f32_e32 v173, v173, v174
	ds_bpermute_b32 v174, v170, v173
	s_waitcnt lgkmcnt(0)
	v_add_f32_e32 v173, v173, v174
	ds_bpermute_b32 v174, v171, v173
	s_and_saveexec_b64 s[30:31], vcc
	s_cbranch_execz .LBB0_683
	s_waitcnt lgkmcnt(0)
	v_add_f32_e32 v173, v173, v174
	ds_write_b32 v172, v173 offset:2560
